# th5 plus sc1 (write-through) on the 16 GEMM2 residual-epilogue stores so the grid barrier's L2 writeback has less to flush
# speedup vs baseline: 1.0143x; 1.0129x over previous
.LBB0_835:
	v_and_b32_e32 v153, 64, v208
	v_xor_b32_e32 v152, 16, v208
	v_add_u32_e32 v154, 64, v153
	v_cmp_lt_i32_e32 vcc, v152, v154
	v_lshl_add_u32 v151, s6, 8, v146
	v_lshl_or_b32 v2, s17, 9, v149
	v_readlane_b32 s2, v254, 39
	v_cndmask_b32_e32 v152, v208, v152, vcc
	v_lshl_add_u32 v2, v151, 12, v2
	v_and_b32_e32 v228, -16, v151
	v_lshlrev_b32_e32 v228, 12, v228
	v_lshrrev_b32_e32 v229, 6, v149
	v_lshlrev_b32_e32 v229, 10, v229
	v_lshl_or_b32 v229, s17, 13, v229
	v_and_b32_e32 v230, 15, v151
	v_lshl_or_b32 v229, v230, 6, v229
	v_bfe_u32 v230, v149, 4, 2
	v_lshrrev_b32_e32 v231, 2, v151
	v_and_b32_e32 v231, 2, v231
	v_xor_b32_e32 v230, v230, v231
	v_lshl_or_b32 v229, v230, 4, v229
	v_add_u32_e32 v229, 0x800, v229
	v_add_u32_e32 v2, v228, v229
	v_readlane_b32 s3, v254, 40
	v_lshlrev_b32_e32 v153, 2, v152
	v_xor_b32_e32 v152, 32, v208
	v_cmp_lt_i32_e32 vcc, v152, v154
	s_nop 1
	global_load_dwordx4 v[154:157], v2, s[2:3] offset:-2048
	global_load_dwordx4 v[158:161], v2, s[2:3] offset:2048
	v_lshl_add_u64 v[144:145], s[2:3], 0, v[2:3]
	v_cndmask_b32_e32 v152, v208, v152, vcc
	v_lshlrev_b32_e32 v152, 2, v152
	s_mov_b32 s99, 0
	s_mov_b32 s98, 0x10000
	v_lshl_add_u64 v[228:229], v[144:145], 0, s[98:99]
	global_load_dwordx4 v[168:171], v[228:229], off offset:2048
	global_load_dwordx4 v[172:175], v[228:229], off offset:-2048
	s_mov_b32 s98, 0x20000
	v_lshl_add_u64 v[230:231], v[144:145], 0, s[98:99]
	global_load_dwordx4 v[176:179], v[230:231], off offset:2048
	global_load_dwordx4 v[180:183], v[230:231], off offset:-2048
	s_mov_b32 s98, 0x30000
	v_lshl_add_u64 v[232:233], v[144:145], 0, s[98:99]
	global_load_dwordx4 v[184:187], v[232:233], off offset:2048
	global_load_dwordx4 v[188:191], v[232:233], off offset:-2048
	s_mov_b32 s98, 0x80000
	v_lshl_add_u64 v[234:235], v[144:145], 0, s[98:99]
	global_load_dwordx4 v[192:195], v[234:235], off offset:-2048
	global_load_dwordx4 v[196:199], v[234:235], off offset:2048
	s_mov_b32 s98, 0x90000
	v_lshl_add_u64 v[236:237], v[144:145], 0, s[98:99]
	global_load_dwordx4 v[200:203], v[236:237], off offset:2048
	global_load_dwordx4 v[204:207], v[236:237], off offset:-2048
	s_mov_b32 s98, 0xa0000
	v_lshl_add_u64 v[238:239], v[144:145], 0, s[98:99]
	global_load_dwordx4 v[212:215], v[238:239], off offset:2048
	global_load_dwordx4 v[216:219], v[238:239], off offset:-2048
	s_mov_b32 s98, 0xb0000
	v_lshl_add_u64 v[240:241], v[144:145], 0, s[98:99]
	global_load_dwordx4 v[220:223], v[240:241], off offset:2048
	global_load_dwordx4 v[224:227], v[240:241], off offset:-2048
	s_waitcnt vmcnt(14)
	v_lshlrev_b32_e32 v162, 16, v154
	v_and_b32_e32 v163, 0xffff0000, v154
	v_pk_fma_f32 v[162:163], v[128:129], s[14:15], v[162:163]
	v_lshlrev_b32_e32 v154, 16, v155
	v_cvt_pk_bf16_f32 v128, v162, v163
	v_fma_f32 v162, v162, v162, 0
	v_and_b32_e32 v155, 0xffff0000, v155
	v_fmac_f32_e32 v162, v163, v163
	v_pk_fma_f32 v[130:131], v[130:131], s[14:15], v[154:155]
	s_nop 0
	v_fmac_f32_e32 v162, v130, v130
	v_cvt_pk_bf16_f32 v129, v130, v131
	v_fmac_f32_e32 v162, v131, v131
	v_lshlrev_b32_e32 v130, 16, v156
	v_and_b32_e32 v131, 0xffff0000, v156
	v_pk_fma_f32 v[124:125], v[124:125], s[14:15], v[130:131]
	s_nop 0
	v_fmac_f32_e32 v162, v124, v124
	v_cvt_pk_bf16_f32 v130, v124, v125
	v_fmac_f32_e32 v162, v125, v125
	v_lshlrev_b32_e32 v124, 16, v157
	v_and_b32_e32 v125, 0xffff0000, v157
	v_pk_fma_f32 v[124:125], v[126:127], s[14:15], v[124:125]
	s_nop 0
	v_fmac_f32_e32 v162, v124, v124
	v_cvt_pk_bf16_f32 v131, v124, v125
	v_fmac_f32_e32 v162, v125, v125
	v_lshlrev_b32_e32 v124, 16, v158
	v_and_b32_e32 v125, 0xffff0000, v158
	v_pk_fma_f32 v[124:125], v[120:121], s[14:15], v[124:125]
	s_nop 0
	v_fmac_f32_e32 v162, v124, v124
	v_cvt_pk_bf16_f32 v120, v124, v125
	v_fmac_f32_e32 v162, v125, v125
	v_lshlrev_b32_e32 v124, 16, v159
	v_and_b32_e32 v125, 0xffff0000, v159
	v_pk_fma_f32 v[122:123], v[122:123], s[14:15], v[124:125]
	s_nop 0
	v_fmac_f32_e32 v162, v122, v122
	v_cvt_pk_bf16_f32 v121, v122, v123
	v_fmac_f32_e32 v162, v123, v123
	v_lshlrev_b32_e32 v122, 16, v160
	v_and_b32_e32 v123, 0xffff0000, v160
	v_pk_fma_f32 v[116:117], v[116:117], s[14:15], v[122:123]
	s_nop 0
	v_fmac_f32_e32 v162, v116, v116
	v_cvt_pk_bf16_f32 v122, v116, v117
	v_fmac_f32_e32 v162, v117, v117
	v_lshlrev_b32_e32 v116, 16, v161
	v_and_b32_e32 v117, 0xffff0000, v161
	v_pk_fma_f32 v[116:117], v[118:119], s[14:15], v[116:117]
	s_nop 0
	v_fmac_f32_e32 v162, v116, v116
	v_fmac_f32_e32 v162, v117, v117
	v_cvt_pk_bf16_f32 v123, v116, v117
	global_store_dwordx4 v2, v[128:131], s[2:3] offset:-2048 sc1
	global_store_dwordx4 v2, v[120:123], s[2:3] offset:2048 sc1
	ds_bpermute_b32 v2, v153, v162
	s_mov_b32 s2, 0x10000
	v_add_co_u32_e32 v124, vcc, s2, v144
	s_mov_b32 s2, 0x20000
	s_waitcnt lgkmcnt(0)
	v_add_f32_e32 v2, v162, v2
	ds_bpermute_b32 v116, v152, v2
	v_addc_co_u32_e32 v125, vcc, 0, v145, vcc
	s_waitcnt lgkmcnt(0)
	v_add_f32_e32 v2, v2, v116
	s_waitcnt vmcnt(14)
	v_lshlrev_b32_e32 v126, 16, v172
	v_and_b32_e32 v127, 0xffff0000, v172
	v_pk_fma_f32 v[126:127], v[112:113], s[14:15], v[126:127]
	v_lshlrev_b32_e32 v120, 16, v173
	v_cvt_pk_bf16_f32 v112, v126, v127
	v_fma_f32 v126, v126, v126, 0
	v_and_b32_e32 v121, 0xffff0000, v173
	v_fmac_f32_e32 v126, v127, v127
	v_pk_fma_f32 v[114:115], v[114:115], s[14:15], v[120:121]
	s_nop 0
	v_fmac_f32_e32 v126, v114, v114
	v_cvt_pk_bf16_f32 v113, v114, v115
	v_fmac_f32_e32 v126, v115, v115
	v_lshlrev_b32_e32 v114, 16, v174
	v_and_b32_e32 v115, 0xffff0000, v174
	v_pk_fma_f32 v[108:109], v[108:109], s[14:15], v[114:115]
	s_nop 0
	v_fmac_f32_e32 v126, v108, v108
	v_cvt_pk_bf16_f32 v114, v108, v109
	v_fmac_f32_e32 v126, v109, v109
	v_lshlrev_b32_e32 v108, 16, v175
	v_and_b32_e32 v109, 0xffff0000, v175
	v_pk_fma_f32 v[108:109], v[110:111], s[14:15], v[108:109]
	v_add_co_u32_e32 v110, vcc, s2, v144
	v_fmac_f32_e32 v126, v108, v108
	v_cvt_pk_bf16_f32 v115, v108, v109
	v_fmac_f32_e32 v126, v109, v109
	v_lshlrev_b32_e32 v108, 16, v168
	v_and_b32_e32 v109, 0xffff0000, v168
	v_pk_fma_f32 v[108:109], v[104:105], s[14:15], v[108:109]
	v_addc_co_u32_e32 v111, vcc, 0, v145, vcc
	v_fmac_f32_e32 v126, v108, v108
	v_cvt_pk_bf16_f32 v104, v108, v109
	v_fmac_f32_e32 v126, v109, v109
	v_lshlrev_b32_e32 v108, 16, v169
	v_and_b32_e32 v109, 0xffff0000, v169
	v_pk_fma_f32 v[106:107], v[106:107], s[14:15], v[108:109]
	s_mov_b32 s2, 0x30000
	v_fmac_f32_e32 v126, v106, v106
	v_cvt_pk_bf16_f32 v105, v106, v107
	v_fmac_f32_e32 v126, v107, v107
	v_lshlrev_b32_e32 v106, 16, v170
	v_and_b32_e32 v107, 0xffff0000, v170
	v_pk_fma_f32 v[100:101], v[100:101], s[14:15], v[106:107]
	s_nop 0
	v_fmac_f32_e32 v126, v100, v100
	v_cvt_pk_bf16_f32 v106, v100, v101
	v_fmac_f32_e32 v126, v101, v101
	v_lshlrev_b32_e32 v100, 16, v171
	v_and_b32_e32 v101, 0xffff0000, v171
	v_pk_fma_f32 v[100:101], v[102:103], s[14:15], v[100:101]
	s_nop 0
	v_cvt_pk_bf16_f32 v107, v100, v101
	global_store_dwordx4 v[124:125], v[112:115], off offset:-2048 sc1
	global_store_dwordx4 v[124:125], v[104:107], off offset:2048 sc1
	s_nop 0
	v_fmac_f32_e32 v126, v100, v100
	v_fmac_f32_e32 v126, v101, v101
	ds_bpermute_b32 v100, v153, v126
	s_waitcnt lgkmcnt(0)
	v_add_f32_e32 v100, v126, v100
	ds_bpermute_b32 v101, v152, v100
	s_waitcnt vmcnt(14)
	v_lshlrev_b32_e32 v112, 16, v180
	v_and_b32_e32 v113, 0xffff0000, v180
	v_pk_fma_f32 v[112:113], v[96:97], s[14:15], v[112:113]
	v_lshlrev_b32_e32 v106, 16, v181
	v_cvt_pk_bf16_f32 v96, v112, v113
	v_fma_f32 v112, v112, v112, 0
	v_and_b32_e32 v107, 0xffff0000, v181
	v_fmac_f32_e32 v112, v113, v113
	v_pk_fma_f32 v[98:99], v[98:99], s[14:15], v[106:107]
	s_nop 0
	v_fmac_f32_e32 v112, v98, v98
	v_cvt_pk_bf16_f32 v97, v98, v99
	v_fmac_f32_e32 v112, v99, v99
	v_lshlrev_b32_e32 v98, 16, v182
	v_and_b32_e32 v99, 0xffff0000, v182
	v_pk_fma_f32 v[92:93], v[92:93], s[14:15], v[98:99]
	s_nop 0
	v_fmac_f32_e32 v112, v92, v92
	v_cvt_pk_bf16_f32 v98, v92, v93
	v_fmac_f32_e32 v112, v93, v93
	v_lshlrev_b32_e32 v92, 16, v183
	v_and_b32_e32 v93, 0xffff0000, v183
	v_pk_fma_f32 v[92:93], v[94:95], s[14:15], v[92:93]
	s_nop 0
	v_fmac_f32_e32 v112, v92, v92
	v_cvt_pk_bf16_f32 v99, v92, v93
	v_fmac_f32_e32 v112, v93, v93
	v_lshlrev_b32_e32 v92, 16, v176
	v_and_b32_e32 v93, 0xffff0000, v176
	v_pk_fma_f32 v[92:93], v[88:89], s[14:15], v[92:93]
	s_nop 0
	v_fmac_f32_e32 v112, v92, v92
	v_cvt_pk_bf16_f32 v88, v92, v93
	v_fmac_f32_e32 v112, v93, v93
	v_lshlrev_b32_e32 v92, 16, v177
	v_and_b32_e32 v93, 0xffff0000, v177
	v_pk_fma_f32 v[90:91], v[90:91], s[14:15], v[92:93]
	v_add_co_u32_e32 v92, vcc, s2, v144
	v_fmac_f32_e32 v112, v90, v90
	v_cvt_pk_bf16_f32 v89, v90, v91
	v_fmac_f32_e32 v112, v91, v91
	v_lshlrev_b32_e32 v90, 16, v178
	v_and_b32_e32 v91, 0xffff0000, v178
	v_pk_fma_f32 v[84:85], v[84:85], s[14:15], v[90:91]
	v_addc_co_u32_e32 v93, vcc, 0, v145, vcc
	v_fmac_f32_e32 v112, v84, v84
	v_cvt_pk_bf16_f32 v90, v84, v85
	v_fmac_f32_e32 v112, v85, v85
	v_lshlrev_b32_e32 v84, 16, v179
	v_and_b32_e32 v85, 0xffff0000, v179
	v_pk_fma_f32 v[84:85], v[86:87], s[14:15], v[84:85]
	s_mov_b32 s2, 0x80000
	v_fmac_f32_e32 v112, v84, v84
	v_fmac_f32_e32 v112, v85, v85
	v_cvt_pk_bf16_f32 v91, v84, v85
	ds_bpermute_b32 v84, v153, v112
	global_store_dwordx4 v[110:111], v[96:99], off offset:-2048 sc1
	global_store_dwordx4 v[110:111], v[88:91], off offset:2048 sc1
	s_waitcnt lgkmcnt(0)
	v_add_f32_e32 v94, v112, v84
	ds_bpermute_b32 v95, v152, v94
	s_waitcnt vmcnt(14)
	v_lshlrev_b32_e32 v96, 16, v188
	v_and_b32_e32 v97, 0xffff0000, v188
	v_pk_fma_f32 v[96:97], v[80:81], s[14:15], v[96:97]
	v_lshlrev_b32_e32 v88, 16, v189
	v_cvt_pk_bf16_f32 v80, v96, v97
	v_fma_f32 v96, v96, v96, 0
	v_and_b32_e32 v89, 0xffff0000, v189
	v_fmac_f32_e32 v96, v97, v97
	v_pk_fma_f32 v[82:83], v[82:83], s[14:15], v[88:89]
	s_nop 0
	v_fmac_f32_e32 v96, v82, v82
	v_cvt_pk_bf16_f32 v81, v82, v83
	v_fmac_f32_e32 v96, v83, v83
	v_lshlrev_b32_e32 v82, 16, v190
	v_and_b32_e32 v83, 0xffff0000, v190
	v_pk_fma_f32 v[76:77], v[76:77], s[14:15], v[82:83]
	s_nop 0
	v_fmac_f32_e32 v96, v76, v76
	v_cvt_pk_bf16_f32 v82, v76, v77
	v_fmac_f32_e32 v96, v77, v77
	v_lshlrev_b32_e32 v76, 16, v191
	v_and_b32_e32 v77, 0xffff0000, v191
	v_pk_fma_f32 v[76:77], v[78:79], s[14:15], v[76:77]
	v_add_co_u32_e32 v78, vcc, s2, v144
	v_fmac_f32_e32 v96, v76, v76
	v_cvt_pk_bf16_f32 v83, v76, v77
	v_fmac_f32_e32 v96, v77, v77
	v_lshlrev_b32_e32 v76, 16, v184
	v_and_b32_e32 v77, 0xffff0000, v184
	v_pk_fma_f32 v[76:77], v[72:73], s[14:15], v[76:77]
	v_addc_co_u32_e32 v79, vcc, 0, v145, vcc
	v_fmac_f32_e32 v96, v76, v76
	v_cvt_pk_bf16_f32 v72, v76, v77
	v_fmac_f32_e32 v96, v77, v77
	v_lshlrev_b32_e32 v76, 16, v185
	v_and_b32_e32 v77, 0xffff0000, v185
	v_pk_fma_f32 v[74:75], v[74:75], s[14:15], v[76:77]
	s_mov_b32 s2, 0x90000
	v_fmac_f32_e32 v96, v74, v74
	v_cvt_pk_bf16_f32 v73, v74, v75
	v_fmac_f32_e32 v96, v75, v75
	v_lshlrev_b32_e32 v74, 16, v186
	v_and_b32_e32 v75, 0xffff0000, v186
	v_pk_fma_f32 v[68:69], v[68:69], s[14:15], v[74:75]
	s_nop 0
	v_fmac_f32_e32 v96, v68, v68
	v_cvt_pk_bf16_f32 v74, v68, v69
	v_fmac_f32_e32 v96, v69, v69
	v_lshlrev_b32_e32 v68, 16, v187
	v_and_b32_e32 v69, 0xffff0000, v187
	v_pk_fma_f32 v[68:69], v[70:71], s[14:15], v[68:69]
	s_nop 0
	v_cvt_pk_bf16_f32 v75, v68, v69
	global_store_dwordx4 v[92:93], v[80:83], off offset:-2048 sc1
	global_store_dwordx4 v[92:93], v[72:75], off offset:2048 sc1
	v_fmac_f32_e32 v96, v68, v68
	v_fmac_f32_e32 v96, v69, v69
	ds_bpermute_b32 v68, v153, v96
	s_waitcnt lgkmcnt(0)
	v_add_f32_e32 v68, v96, v68
	ds_bpermute_b32 v69, v152, v68
	s_waitcnt vmcnt(15)
	v_lshlrev_b32_e32 v80, 16, v192
	v_and_b32_e32 v81, 0xffff0000, v192
	v_pk_fma_f32 v[80:81], v[64:65], s[14:15], v[80:81]
	v_lshlrev_b32_e32 v70, 16, v193
	v_cvt_pk_bf16_f32 v64, v80, v81
	v_fma_f32 v80, v80, v80, 0
	v_and_b32_e32 v71, 0xffff0000, v193
	v_fmac_f32_e32 v80, v81, v81
	v_pk_fma_f32 v[66:67], v[66:67], s[14:15], v[70:71]
	s_nop 0
	v_fmac_f32_e32 v80, v66, v66
	v_cvt_pk_bf16_f32 v65, v66, v67
	v_fmac_f32_e32 v80, v67, v67
	v_lshlrev_b32_e32 v66, 16, v194
	v_and_b32_e32 v67, 0xffff0000, v194
	v_pk_fma_f32 v[60:61], v[60:61], s[14:15], v[66:67]
	s_nop 0
	v_fmac_f32_e32 v80, v60, v60
	v_cvt_pk_bf16_f32 v66, v60, v61
	v_fmac_f32_e32 v80, v61, v61
	v_lshlrev_b32_e32 v60, 16, v195
	v_and_b32_e32 v61, 0xffff0000, v195
	v_pk_fma_f32 v[60:61], v[62:63], s[14:15], v[60:61]
	v_add_co_u32_e32 v62, vcc, s2, v144
	v_fmac_f32_e32 v80, v60, v60
	v_cvt_pk_bf16_f32 v67, v60, v61
	v_fmac_f32_e32 v80, v61, v61
	s_waitcnt vmcnt(14)
	v_lshlrev_b32_e32 v60, 16, v196
	v_and_b32_e32 v61, 0xffff0000, v196
	v_pk_fma_f32 v[60:61], v[56:57], s[14:15], v[60:61]
	v_addc_co_u32_e32 v63, vcc, 0, v145, vcc
	v_fmac_f32_e32 v80, v60, v60
	v_cvt_pk_bf16_f32 v56, v60, v61
	v_fmac_f32_e32 v80, v61, v61
	v_lshlrev_b32_e32 v60, 16, v197
	v_and_b32_e32 v61, 0xffff0000, v197
	v_pk_fma_f32 v[58:59], v[58:59], s[14:15], v[60:61]
	s_mov_b32 s2, 0xa0000
	v_fmac_f32_e32 v80, v58, v58
	v_cvt_pk_bf16_f32 v57, v58, v59
	v_fmac_f32_e32 v80, v59, v59
	v_lshlrev_b32_e32 v58, 16, v198
	v_and_b32_e32 v59, 0xffff0000, v198
	v_pk_fma_f32 v[52:53], v[52:53], s[14:15], v[58:59]
	s_nop 0
	v_fmac_f32_e32 v80, v52, v52
	v_cvt_pk_bf16_f32 v58, v52, v53
	v_fmac_f32_e32 v80, v53, v53
	v_lshlrev_b32_e32 v52, 16, v199
	v_and_b32_e32 v53, 0xffff0000, v199
	v_pk_fma_f32 v[52:53], v[54:55], s[14:15], v[52:53]
	s_nop 0
	v_cvt_pk_bf16_f32 v59, v52, v53
	global_store_dwordx4 v[78:79], v[64:67], off offset:-2048 sc1
	global_store_dwordx4 v[78:79], v[56:59], off offset:2048 sc1
	s_nop 0
	v_fmac_f32_e32 v80, v52, v52
	v_fmac_f32_e32 v80, v53, v53
	ds_bpermute_b32 v52, v153, v80
	s_waitcnt lgkmcnt(0)
	v_add_f32_e32 v52, v80, v52
	ds_bpermute_b32 v53, v152, v52
	s_waitcnt vmcnt(14)
	v_lshlrev_b32_e32 v64, 16, v204
	v_and_b32_e32 v65, 0xffff0000, v204
	v_pk_fma_f32 v[64:65], v[48:49], s[14:15], v[64:65]
	v_lshlrev_b32_e32 v58, 16, v205
	v_cvt_pk_bf16_f32 v48, v64, v65
	v_fma_f32 v64, v64, v64, 0
	v_and_b32_e32 v59, 0xffff0000, v205
	v_fmac_f32_e32 v64, v65, v65
	v_pk_fma_f32 v[50:51], v[50:51], s[14:15], v[58:59]
	s_nop 0
	v_fmac_f32_e32 v64, v50, v50
	v_cvt_pk_bf16_f32 v49, v50, v51
	v_fmac_f32_e32 v64, v51, v51
	v_lshlrev_b32_e32 v50, 16, v206
	v_and_b32_e32 v51, 0xffff0000, v206
	v_pk_fma_f32 v[44:45], v[44:45], s[14:15], v[50:51]
	s_nop 0
	v_fmac_f32_e32 v64, v44, v44
	v_cvt_pk_bf16_f32 v50, v44, v45
	v_fmac_f32_e32 v64, v45, v45
	v_lshlrev_b32_e32 v44, 16, v207
	v_and_b32_e32 v45, 0xffff0000, v207
	v_pk_fma_f32 v[44:45], v[46:47], s[14:15], v[44:45]
	v_add_co_u32_e32 v46, vcc, s2, v144
	v_fmac_f32_e32 v64, v44, v44
	v_cvt_pk_bf16_f32 v51, v44, v45
	v_fmac_f32_e32 v64, v45, v45
	v_lshlrev_b32_e32 v44, 16, v200
	v_and_b32_e32 v45, 0xffff0000, v200
	v_pk_fma_f32 v[44:45], v[40:41], s[14:15], v[44:45]
	v_addc_co_u32_e32 v47, vcc, 0, v145, vcc
	v_fmac_f32_e32 v64, v44, v44
	v_cvt_pk_bf16_f32 v40, v44, v45
	v_fmac_f32_e32 v64, v45, v45
	v_lshlrev_b32_e32 v44, 16, v201
	v_and_b32_e32 v45, 0xffff0000, v201
	v_pk_fma_f32 v[42:43], v[42:43], s[14:15], v[44:45]
	s_mov_b32 s2, 0xb0000
	v_fmac_f32_e32 v64, v42, v42
	v_cvt_pk_bf16_f32 v41, v42, v43
	v_fmac_f32_e32 v64, v43, v43
	v_lshlrev_b32_e32 v42, 16, v202
	v_and_b32_e32 v43, 0xffff0000, v202
	v_pk_fma_f32 v[36:37], v[36:37], s[14:15], v[42:43]
	s_nop 0
	v_fmac_f32_e32 v64, v36, v36
	v_cvt_pk_bf16_f32 v42, v36, v37
	v_fmac_f32_e32 v64, v37, v37
	v_lshlrev_b32_e32 v36, 16, v203
	v_and_b32_e32 v37, 0xffff0000, v203
	v_pk_fma_f32 v[36:37], v[38:39], s[14:15], v[36:37]
	s_nop 0
	v_cvt_pk_bf16_f32 v43, v36, v37
	global_store_dwordx4 v[62:63], v[48:51], off offset:-2048 sc1
	global_store_dwordx4 v[62:63], v[40:43], off offset:2048 sc1
	s_nop 0
	v_fmac_f32_e32 v64, v36, v36
	v_fmac_f32_e32 v64, v37, v37
	ds_bpermute_b32 v36, v153, v64
	s_waitcnt lgkmcnt(0)
	v_add_f32_e32 v36, v64, v36
	ds_bpermute_b32 v37, v152, v36
	s_waitcnt vmcnt(14)
	v_lshlrev_b32_e32 v48, 16, v216
	v_and_b32_e32 v49, 0xffff0000, v216
	v_pk_fma_f32 v[48:49], v[32:33], s[14:15], v[48:49]
	v_lshlrev_b32_e32 v42, 16, v217
	v_cvt_pk_bf16_f32 v32, v48, v49
	v_fma_f32 v48, v48, v48, 0
	v_and_b32_e32 v43, 0xffff0000, v217
	v_fmac_f32_e32 v48, v49, v49
	v_pk_fma_f32 v[34:35], v[34:35], s[14:15], v[42:43]
	s_nop 0
	v_fmac_f32_e32 v48, v34, v34
	v_cvt_pk_bf16_f32 v33, v34, v35
	v_fmac_f32_e32 v48, v35, v35
	v_lshlrev_b32_e32 v34, 16, v218
	v_and_b32_e32 v35, 0xffff0000, v218
	v_pk_fma_f32 v[28:29], v[28:29], s[14:15], v[34:35]
	s_nop 0
	v_fmac_f32_e32 v48, v28, v28
	v_cvt_pk_bf16_f32 v34, v28, v29
	v_fmac_f32_e32 v48, v29, v29
	v_lshlrev_b32_e32 v28, 16, v219
	v_and_b32_e32 v29, 0xffff0000, v219
	v_pk_fma_f32 v[28:29], v[30:31], s[14:15], v[28:29]
	s_nop 0
	v_fmac_f32_e32 v48, v28, v28
	v_cvt_pk_bf16_f32 v35, v28, v29
	v_fmac_f32_e32 v48, v29, v29
	v_lshlrev_b32_e32 v28, 16, v212
	v_and_b32_e32 v29, 0xffff0000, v212
	v_pk_fma_f32 v[28:29], v[24:25], s[14:15], v[28:29]
	s_nop 0
	v_fmac_f32_e32 v48, v28, v28
	v_cvt_pk_bf16_f32 v24, v28, v29
	v_fmac_f32_e32 v48, v29, v29
	v_lshlrev_b32_e32 v28, 16, v213
	v_and_b32_e32 v29, 0xffff0000, v213
	v_pk_fma_f32 v[26:27], v[26:27], s[14:15], v[28:29]
	v_add_co_u32_e32 v28, vcc, s2, v144
	v_fmac_f32_e32 v48, v26, v26
	v_cvt_pk_bf16_f32 v25, v26, v27
	v_fmac_f32_e32 v48, v27, v27
	v_lshlrev_b32_e32 v26, 16, v214
	v_and_b32_e32 v27, 0xffff0000, v214
	v_pk_fma_f32 v[20:21], v[20:21], s[14:15], v[26:27]
	v_addc_co_u32_e32 v29, vcc, 0, v145, vcc
	v_fmac_f32_e32 v48, v20, v20
	v_cvt_pk_bf16_f32 v26, v20, v21
	v_fmac_f32_e32 v48, v21, v21
	v_lshlrev_b32_e32 v20, 16, v215
	v_and_b32_e32 v21, 0xffff0000, v215
	v_pk_fma_f32 v[20:21], v[22:23], s[14:15], v[20:21]
	s_nop 0
	v_fmac_f32_e32 v48, v20, v20
	v_fmac_f32_e32 v48, v21, v21
	v_cvt_pk_bf16_f32 v27, v20, v21
	ds_bpermute_b32 v20, v153, v48
	global_store_dwordx4 v[46:47], v[32:35], off offset:-2048 sc1
	global_store_dwordx4 v[46:47], v[24:27], off offset:2048 sc1
	s_waitcnt lgkmcnt(0)
	v_add_f32_e32 v30, v48, v20
	ds_bpermute_b32 v31, v152, v30
	s_waitcnt vmcnt(14)
	v_lshlrev_b32_e32 v32, 16, v224
	v_and_b32_e32 v33, 0xffff0000, v224
	v_pk_fma_f32 v[32:33], v[16:17], s[14:15], v[32:33]
	v_lshlrev_b32_e32 v24, 16, v225
	v_cvt_pk_bf16_f32 v16, v32, v33
	v_fma_f32 v32, v32, v32, 0
	v_and_b32_e32 v25, 0xffff0000, v225
	v_fmac_f32_e32 v32, v33, v33
	v_pk_fma_f32 v[18:19], v[18:19], s[14:15], v[24:25]
	s_nop 0
	v_fmac_f32_e32 v32, v18, v18
	v_cvt_pk_bf16_f32 v17, v18, v19
	v_fmac_f32_e32 v32, v19, v19
	v_lshlrev_b32_e32 v18, 16, v226
	v_and_b32_e32 v19, 0xffff0000, v226
	v_pk_fma_f32 v[12:13], v[12:13], s[14:15], v[18:19]
	s_nop 0
	v_fmac_f32_e32 v32, v12, v12
	v_cvt_pk_bf16_f32 v18, v12, v13
	v_fmac_f32_e32 v32, v13, v13
	v_lshlrev_b32_e32 v12, 16, v227
	v_and_b32_e32 v13, 0xffff0000, v227
	v_pk_fma_f32 v[12:13], v[14:15], s[14:15], v[12:13]
	s_nop 0
	v_fmac_f32_e32 v32, v12, v12
	v_cvt_pk_bf16_f32 v19, v12, v13
	v_fmac_f32_e32 v32, v13, v13
	v_lshlrev_b32_e32 v12, 16, v220
	v_and_b32_e32 v13, 0xffff0000, v220
	v_pk_fma_f32 v[12:13], v[8:9], s[14:15], v[12:13]
	s_nop 0
	v_fmac_f32_e32 v32, v12, v12
	v_cvt_pk_bf16_f32 v8, v12, v13
	v_fmac_f32_e32 v32, v13, v13
	v_lshlrev_b32_e32 v12, 16, v221
	v_and_b32_e32 v13, 0xffff0000, v221
	v_pk_fma_f32 v[10:11], v[10:11], s[14:15], v[12:13]
	s_nop 0
	v_fmac_f32_e32 v32, v10, v10
	v_cvt_pk_bf16_f32 v9, v10, v11
	v_fmac_f32_e32 v32, v11, v11
	v_lshlrev_b32_e32 v10, 16, v222
	v_and_b32_e32 v11, 0xffff0000, v222
	v_pk_fma_f32 v[4:5], v[4:5], s[14:15], v[10:11]
	s_nop 0
	v_fmac_f32_e32 v32, v4, v4
	v_cvt_pk_bf16_f32 v10, v4, v5
	v_fmac_f32_e32 v32, v5, v5
	v_lshlrev_b32_e32 v4, 16, v223
	v_and_b32_e32 v5, 0xffff0000, v223
	v_pk_fma_f32 v[4:5], v[6:7], s[14:15], v[4:5]
	s_nop 0
	v_fmac_f32_e32 v32, v4, v4
	v_fmac_f32_e32 v32, v5, v5
	v_cvt_pk_bf16_f32 v11, v4, v5
	ds_bpermute_b32 v4, v153, v32
	global_store_dwordx4 v[28:29], v[16:19], off offset:-2048 sc1
	global_store_dwordx4 v[28:29], v[8:11], off offset:2048 sc1
	s_waitcnt lgkmcnt(0)
	v_add_f32_e32 v4, v32, v4
	ds_bpermute_b32 v5, v152, v4
	s_and_saveexec_b64 s[2:3], s[38:39]
	v_add_f32_e32 v2, v30, v31
	v_add_f32_e32 v6, v52, v53
	v_add_f32_e32 v7, v94, v95
	v_cndmask_b32_e64 v2, v2, v6, s[42:43]
	v_cndmask_b32_e64 v2, v2, v7, s[40:41]
	s_or_b64 exec, exec, s[2:3]
	v_add_f32_e32 v8, v36, v37
	s_waitcnt lgkmcnt(0)
	v_add_f32_e32 v4, v4, v5
	v_add_f32_e32 v7, v68, v69
	v_cndmask_b32_e64 v4, v4, v8, s[42:43]
	v_add_f32_e32 v6, v100, v101
	v_cndmask_b32_e64 v4, v4, v7, s[40:41]
	v_cndmask_b32_e64 v6, v4, v6, s[36:37]
	v_add_u32_e32 v4, v148, v151
	v_ashrrev_i32_e32 v5, 31, v4
	v_readlane_b32 s2, v252, 45
	v_lshlrev_b64 v[4:5], 7, v[4:5]
	v_readlane_b32 s3, v252, 46
	s_and_b64 vcc, exec, s[44:45]
	s_nop 0
	v_lshl_add_u64 v[4:5], s[2:3], 0, v[4:5]
	s_lshl_b32 s2, s17, 2
	s_ashr_i32 s3, s2, 31
	v_lshl_add_u64 v[4:5], s[2:3], 2, v[4:5]
	v_readlane_b32 s2, v255, 9
	v_readlane_b32 s3, v255, 10
	s_nop 1
	v_lshl_add_u64 v[4:5], v[4:5], 0, s[2:3]
	s_mov_b64 s[2:3], -1
	global_store_dword v[4:5], v2, off
	global_store_dword v[4:5], v6, off offset:2048
	s_cbranch_vccnz .LBB0_820
	s_andn2_b64 vcc, exec, s[12:13]
	s_cbranch_vccnz .LBB0_819
	s_barrier
	s_branch .LBB0_819
